# epilogue-entry vmcnt(0) drains relaxed to lgkmcnt(0) (next unit tile DMAs stay in flight); + no setprio flips; + x->bf16 loop de-serialized
# baseline (speedup 1.0000x reference)
.LBB0_859:
	v_mov_b32_e32 v189, v239
	v_mov_b32_e32 v191, v241
	s_cmp_lt_i32 s85, 2
	s_mov_b64 s[0:1], -1
	s_cbranch_scc0 .LBB0_1183
	s_lshl_b32 s0, s75, 6
	s_add_i32 s0, s0, 0
	s_add_i32 s0, s0, 0x21400
	v_mov_b32_e32 v2, s0
	s_waitcnt lgkmcnt(0)
	ds_read_b96 v[134:136], v2
	v_mov_b32_e32 v2, s73
	ds_read_b32 v2, v2
	s_mov_b64 s[6:7], -1
	s_mov_b64 s[0:1], 0
	s_waitcnt lgkmcnt(0)
	v_readfirstlane_b32 s42, v134
	v_readfirstlane_b32 s36, v135
	v_readfirstlane_b32 s12, v2
	v_mov_b32_e32 v2, s77
	ds_read_b32 v2, v2
	v_readfirstlane_b32 s37, v136
	s_cmp_lt_i32 s42, 3
	s_mov_b64 s[14:15], 0
	s_waitcnt lgkmcnt(0)
	v_readfirstlane_b32 s13, v2
	s_cbranch_scc1 .LBB0_993
	s_cmp_gt_i32 s42, 3
	s_cbranch_scc0 .LBB0_966
	s_cmp_gt_i32 s42, 4
	s_cbranch_scc0 .LBB0_892
	s_cmp_eq_u32 s42, 5
	s_mov_b64 s[14:15], -1
	s_cbranch_scc0 .LBB0_891
	s_add_u32 s6, s12, 0x41900000
	s_addc_u32 s7, s13, 0
	s_add_u32 s8, s12, 0x2af00000
	s_addc_u32 s9, s13, 0
	s_lshl_b32 s10, s4, 8
	v_readlane_b32 s11, v255, 18
	s_add_i32 s10, s10, s11
	v_add_u32_e32 v162, s10, v189
	s_lshl_b32 s10, s3, 8
	s_or_b32 s10, s10, s70
	v_lshl_add_u32 v4, v191, 3, s10
	v_ashrrev_i32_e32 v5, 31, v4
	v_lshlrev_b64 v[158:159], 1, v[4:5]
	v_lshl_add_u64 v[134:135], s[12:13], 0, v[158:159]
	s_mov_b64 s[10:11], 0x3f500000
	v_lshl_add_u64 v[160:161], v[134:135], 0, s[10:11]
	v_add_u32_e32 v134, 16, v162
	s_movk_i32 s14, 0x3000
	v_ashrrev_i32_e32 v135, 31, v134
	v_mov_b64_e32 v[136:137], s[8:9]
	v_mad_i64_i32 v[138:139], s[10:11], v134, s14, v[136:137]
	v_lshlrev_b64 v[168:169], 12, v[134:135]
	v_add_u32_e32 v134, 32, v162
	v_lshl_add_u64 v[176:177], v[138:139], 0, v[158:159]
	s_movk_i32 s15, 0x2000
	v_ashrrev_i32_e32 v135, 31, v134
	v_add_co_u32_e32 v138, vcc, s15, v176
	v_lshlrev_b64 v[166:167], 12, v[134:135]
	s_nop 0
	v_addc_co_u32_e32 v139, vcc, 0, v177, vcc
	v_lshl_add_u64 v[180:181], v[160:161], 0, v[166:167]
	global_load_dwordx4 v[150:153], v[138:139], off
	global_load_dwordx4 v[146:149], v[180:181], off
	v_mad_i64_i32 v[138:139], s[10:11], v134, s14, v[136:137]
	v_lshl_add_u64 v[178:179], v[138:139], 0, v[158:159]
	v_add_co_u32_e32 v138, vcc, s15, v178
	v_lshl_add_u64 v[174:175], v[160:161], 0, v[168:169]
	s_nop 0
	v_addc_co_u32_e32 v139, vcc, 0, v179, vcc
	global_load_dwordx4 v[142:145], v[138:139], off
	v_add_u32_e32 v138, 48, v162
	v_mad_i64_i32 v[134:135], s[10:11], v138, s14, v[136:137]
	v_ashrrev_i32_e32 v139, 31, v138
	v_lshl_add_u64 v[182:183], v[134:135], 0, v[158:159]
	v_add_co_u32_e32 v134, vcc, 0x2000, v182
	v_lshlrev_b64 v[164:165], 12, v[138:139]
	s_nop 0
	v_addc_co_u32_e32 v135, vcc, 0, v183, vcc
	v_lshl_add_u64 v[184:185], v[160:161], 0, v[164:165]
	global_load_dwordx4 v[154:157], v[174:175], off
	global_load_dwordx4 v[138:141], v[184:185], off
	v_mad_i64_i32 v[172:173], s[10:11], v162, s14, 0
	global_load_dwordx4 v[134:137], v[134:135], off
	s_and_b32 s14, s84, 1
	v_ashrrev_i32_e32 v163, 31, v162
	s_bitcmp1_b32 s84, 0
	v_lshlrev_b64 v[170:171], 12, v[162:163]
	s_cselect_b64 s[10:11], -1, 0
	s_cmp_eq_u32 s14, 0
	s_cbranch_scc1 .LBB0_866
	v_lshl_add_u64 v[186:187], v[160:161], 0, v[170:171]
	global_load_dwordx4 v[204:207], v[186:187], off
	v_lshl_add_u64 v[186:187], s[8:9], 0, v[172:173]
	v_lshl_add_u64 v[186:187], v[186:187], 0, v[158:159]
	v_add_co_u32_e32 v186, vcc, 0x2000, v186
	s_nop 1
	v_addc_co_u32_e32 v187, vcc, 0, v187, vcc
	global_load_dwordx4 v[208:211], v[186:187], off
	s_waitcnt vmcnt(0)
	v_lshlrev_b32_e32 v186, 16, v204
	v_and_b32_e32 v187, 0xffff0000, v204
	v_lshlrev_b32_e32 v204, 16, v205
	v_and_b32_e32 v205, 0xffff0000, v205
	v_lshlrev_b32_e32 v212, 16, v208
	v_and_b32_e32 v213, 0xffff0000, v208
	v_lshlrev_b32_e32 v208, 16, v209
	v_and_b32_e32 v209, 0xffff0000, v209
	v_pk_fma_f32 v[208:209], v[128:129], v[208:209], v[204:205]
	v_pk_fma_f32 v[186:187], v[126:127], v[212:213], v[186:187]
	v_lshlrev_b32_e32 v204, 16, v206
	v_and_b32_e32 v205, 0xffff0000, v206
	v_lshlrev_b32_e32 v206, 16, v207
	v_and_b32_e32 v207, 0xffff0000, v207
	v_lshlrev_b32_e32 v212, 16, v210
	v_and_b32_e32 v213, 0xffff0000, v210
	v_lshlrev_b32_e32 v210, 16, v211
	v_and_b32_e32 v211, 0xffff0000, v211
	v_pk_fma_f32 v[210:211], v[132:133], v[210:211], v[206:207]
	v_pk_fma_f32 v[206:207], v[130:131], v[212:213], v[204:205]
	v_cvt_pk_bf16_f32 v204, v186, v187
	v_lshl_add_u64 v[186:187], s[6:7], 0, v[170:171]
	v_cvt_pk_bf16_f32 v205, v208, v209
	v_cvt_pk_bf16_f32 v206, v206, v207
	v_cvt_pk_bf16_f32 v207, v210, v211
	v_lshl_add_u64 v[186:187], v[186:187], 0, v[158:159]
	global_store_dwordx4 v[186:187], v[204:207], off

.LBB0_966:
	s_and_b64 vcc, exec, s[6:7]
	s_cbranch_vccz .LBB0_992
	v_readlane_b32 s8, v255, 18
	v_lshl_add_u32 v2, v191, 3, s70
	v_lshlrev_b32_e32 v173, 3, v2
	v_add_u32_e32 v5, s8, v189
	v_lshl_add_u32 v4, v5, 2, 0
	s_waitcnt lgkmcnt(0)
	v_add_u32_e32 v134, 0x20800, v4
	v_add_u32_e32 v4, 0x20c00, v4
	ds_read2_b32 v[148:149], v134 offset1:16
	ds_read2_b32 v[146:147], v4 offset1:16
	ds_read2_b32 v[144:145], v134 offset0:32 offset1:48
	ds_read2_b32 v[142:143], v4 offset0:32 offset1:48
	ds_read2_b32 v[140:141], v134 offset0:128 offset1:144
	ds_read2_b32 v[138:139], v4 offset0:128 offset1:144
	ds_read2_b32 v[136:137], v134 offset0:160 offset1:176
	ds_read2_b32 v[134:135], v4 offset0:160 offset1:176
	v_lshl_add_u32 v4, s3, 8, v2
	v_add_u32_e32 v2, 0, v173
	v_add_u32_e32 v150, 0x20000, v2
	ds_read_b128 v[152:155], v150
	ds_read_b128 v[160:163], v150 offset:16
	ds_read_b128 v[164:167], v150 offset:32
	ds_read_b128 v[168:171], v150 offset:48
	v_lshl_add_u32 v2, s4, 8, v5
	s_add_u32 s6, s12, 0x31b00000
	s_addc_u32 s7, s13, 0
	s_waitcnt lgkmcnt(3)
	v_mov_b32_e32 v150, v152
	v_mov_b32_e32 v151, v154
	v_pk_mul_f32 v[150:151], v[150:151], s[72:73] op_sel_hi:[1,0]
	s_waitcnt lgkmcnt(2)
	v_mov_b32_e32 v154, v160
	v_pk_mul_f32 v[156:157], v[150:151], v[150:151]
	s_and_b32 s10, s84, 1
	v_fma_f32 v5, v153, s72, -v156
	v_add_f32_e32 v5, 0x3727c5ac, v5
	v_rsq_f32_e32 v152, v5
	v_fma_f32 v5, v155, s72, -v157
	v_mov_b32_e32 v155, v162
	v_pk_mul_f32 v[158:159], v[154:155], s[72:73] op_sel_hi:[1,0]
	v_add_f32_e32 v5, 0x3727c5ac, v5
	v_pk_mul_f32 v[154:155], v[158:159], v[158:159]
	v_rsq_f32_e32 v153, v5
	v_fma_f32 v5, v161, s72, -v154
	v_add_f32_e32 v5, 0x3727c5ac, v5
	s_waitcnt lgkmcnt(1)
	v_mov_b32_e32 v156, v164
	v_mov_b32_e32 v157, v166
	v_rsq_f32_e32 v154, v5
	v_fma_f32 v5, v163, s72, -v155
	v_pk_mul_f32 v[156:157], v[156:157], s[72:73] op_sel_hi:[1,0]
	v_add_f32_e32 v5, 0x3727c5ac, v5
	v_pk_mul_f32 v[160:161], v[156:157], v[156:157]
	v_rsq_f32_e32 v155, v5
	v_fma_f32 v5, v165, s72, -v160
	v_add_f32_e32 v5, 0x3727c5ac, v5
	s_waitcnt lgkmcnt(0)
	v_mov_b32_e32 v162, v168
	v_mov_b32_e32 v163, v170
	v_rsq_f32_e32 v160, v5
	v_fma_f32 v5, v167, s72, -v161
	v_pk_mul_f32 v[164:165], v[162:163], s[72:73] op_sel_hi:[1,0]
	v_add_f32_e32 v5, 0x3727c5ac, v5
	v_pk_mul_f32 v[162:163], v[164:165], v[164:165]
	v_rsq_f32_e32 v161, v5
	v_fma_f32 v5, v169, s72, -v162
	v_add_f32_e32 v5, 0x3727c5ac, v5
	v_rsq_f32_e32 v162, v5
	v_fma_f32 v5, v171, s72, -v163
	v_add_f32_e32 v5, 0x3727c5ac, v5
	v_rsq_f32_e32 v163, v5
	s_bitcmp1_b32 s84, 0
	s_cselect_b64 s[8:9], -1, 0
	s_cmp_eq_u32 s10, 0
	v_ashrrev_i32_e32 v5, 31, v4
	s_cbranch_scc1 .LBB0_969
	v_pk_fma_f32 v[166:167], v[148:149], v[158:159], v[128:129] op_sel_hi:[0,1,1] neg_lo:[1,0,0] neg_hi:[1,0,0]
	v_pk_fma_f32 v[170:171], v[154:155], v[166:167], v[146:147] op_sel_hi:[1,1,0]
	v_pk_fma_f32 v[166:167], v[148:149], v[164:165], v[132:133] op_sel_hi:[0,1,1] neg_lo:[1,0,0] neg_hi:[1,0,0]
	v_pk_fma_f32 v[168:169], v[148:149], v[150:151], v[126:127] op_sel_hi:[0,1,1] neg_lo:[1,0,0] neg_hi:[1,0,0]
	v_pk_fma_f32 v[174:175], v[148:149], v[156:157], v[130:131] op_sel_hi:[0,1,1] neg_lo:[1,0,0] neg_hi:[1,0,0]
	v_pk_fma_f32 v[176:177], v[162:163], v[166:167], v[146:147] op_sel_hi:[1,1,0]
	v_cvt_pk_bf16_f32 v167, v170, v171
	v_mov_b64_e32 v[170:171], s[6:7]
	s_movk_i32 s10, 0x4800
	v_pk_fma_f32 v[168:169], v[152:153], v[168:169], v[146:147] op_sel_hi:[1,1,0]
	v_pk_fma_f32 v[174:175], v[160:161], v[174:175], v[146:147] op_sel_hi:[1,1,0]
	v_mad_i64_i32 v[170:171], s[10:11], v2, s10, v[170:171]
	v_cvt_pk_bf16_f32 v166, v168, v169
	v_cvt_pk_bf16_f32 v168, v174, v175
	v_cvt_pk_bf16_f32 v169, v176, v177
	v_lshl_add_u64 v[170:171], v[4:5], 1, v[170:171]
	global_store_dwordx4 v[170:171], v[166:169], off

.LBB0_993:
	s_and_b64 vcc, exec, s[6:7]
	s_cbranch_vccz .LBB0_1109
	s_cmp_gt_i32 s42, 0
	s_mov_b64 s[0:1], -1
	s_cbranch_scc0 .LBB0_1107
	s_cmp_gt_i32 s42, 1
	s_cbranch_scc0 .LBB0_1021
	v_readlane_b32 s0, v255, 18
	s_waitcnt lgkmcnt(0)
	v_lshl_add_u32 v135, v191, 3, s70
	v_readlane_b32 s1, v254, 43
	v_add_u32_e32 v5, s0, v189
	v_lshl_add_u32 v2, v5, 3, 0
	v_add_u32_e32 v134, 0x20000, v2
	ds_read2_b64 v[176:179], v134 offset1:16
	v_readlane_b32 s0, v254, 42
	v_lshl_add_u32 v4, s3, 8, v135
	s_add_u32 s6, s12, 0x2af00000
	s_addc_u32 s7, s13, 0
	s_waitcnt lgkmcnt(0)
	v_mul_f32_e32 v2, 0x3a000000, v176
	v_mul_f32_e32 v136, v2, v2
	v_fma_f32 v136, v177, s72, -v136
	v_add_f32_e32 v136, 0x3727c5ac, v136
	ds_read2_b64 v[174:177], v134 offset0:32 offset1:48
	ds_read2_b64 v[170:173], v134 offset0:128 offset1:144
	ds_read2_b64 v[166:169], v134 offset0:160 offset1:176
	v_lshlrev_b32_e32 v134, 2, v135
	v_rsq_f32_e32 v180, v136
	v_add_u32_e32 v135, s0, v134
	v_add_u32_e32 v136, s1, v134
	v_or_b32_e32 v134, 16, v134
	v_add_u32_e32 v137, s0, v134
	v_add_u32_e32 v134, s1, v134
	ds_read_b128 v[154:157], v137
	ds_read_b128 v[150:153], v134
	ds_read_b128 v[162:165], v135
	ds_read_b128 v[146:149], v135 offset:512
	ds_read_b128 v[158:161], v136
	ds_read_b128 v[138:141], v135 offset:528
	ds_read_b128 v[142:145], v136 offset:512
	ds_read_b128 v[134:137], v136 offset:528
	s_cmp_lt_i32 s3, 8
	s_cselect_b64 s[0:1], -1, 0
	s_and_b32 s10, s84, 1
	s_bitcmp1_b32 s84, 0
	v_lshl_add_u32 v181, s4, 8, v5
	s_cselect_b64 s[8:9], -1, 0
	s_cmp_eq_u32 s10, 0
	v_ashrrev_i32_e32 v5, 31, v4
	s_cbranch_scc1 .LBB0_998
	s_waitcnt lgkmcnt(5)
	v_pk_fma_f32 v[182:183], v[2:3], v[164:165], v[128:129] op_sel_hi:[0,1,1] neg_lo:[1,0,0] neg_hi:[1,0,0]
	v_pk_fma_f32 v[184:185], v[2:3], v[162:163], v[126:127] op_sel_hi:[0,1,1] neg_lo:[1,0,0] neg_hi:[1,0,0]
	s_waitcnt lgkmcnt(3)
	v_pk_fma_f32 v[182:183], v[180:181], v[182:183], v[160:161] op_sel_hi:[0,1,1]
	v_pk_fma_f32 v[184:185], v[180:181], v[184:185], v[158:159] op_sel_hi:[0,1,1]
	v_mul_f32_e32 v186, 0xbfb8aa3b, v184
	v_mul_f32_e32 v187, 0xbfb8aa3b, v185
	v_mul_f32_e32 v197, 0xbfb8aa3b, v182
	v_exp_f32_e32 v186, v186
	v_exp_f32_e32 v187, v187
	v_exp_f32_e32 v204, v197
	v_mul_f32_e32 v197, 0xbfb8aa3b, v183
	v_exp_f32_e32 v205, v197
	v_pk_add_f32 v[186:187], v[186:187], 1.0 op_sel_hi:[1,0]
	s_movk_i32 s10, 0x3000
	v_rcp_f32_e32 v186, v186
	v_pk_add_f32 v[204:205], v[204:205], 1.0 op_sel_hi:[1,0]
	v_rcp_f32_e32 v187, v187
	v_rcp_f32_e32 v204, v204
	v_rcp_f32_e32 v205, v205
	v_pk_mul_f32 v[184:185], v[184:185], v[186:187]
	s_nop 0
	v_cndmask_b32_e64 v201, v187, v185, s[0:1]
	v_pk_mul_f32 v[182:183], v[182:183], v[204:205]
	v_cndmask_b32_e64 v203, v186, v184, s[0:1]
	v_pk_fma_f32 v[184:185], v[2:3], v[154:155], v[130:131] op_sel_hi:[0,1,1] neg_lo:[1,0,0] neg_hi:[1,0,0]
	v_cndmask_b32_e64 v197, v205, v183, s[0:1]
	v_cndmask_b32_e64 v199, v204, v182, s[0:1]
	v_pk_fma_f32 v[182:183], v[2:3], v[156:157], v[132:133] op_sel_hi:[0,1,1] neg_lo:[1,0,0] neg_hi:[1,0,0]
	v_pk_fma_f32 v[184:185], v[180:181], v[184:185], v[150:151] op_sel_hi:[0,1,1]
	v_pk_fma_f32 v[182:183], v[180:181], v[182:183], v[152:153] op_sel_hi:[0,1,1]
	v_mul_f32_e32 v186, 0xbfb8aa3b, v184
	v_mul_f32_e32 v187, 0xbfb8aa3b, v185
	v_exp_f32_e32 v186, v186
	v_exp_f32_e32 v187, v187
	v_mul_f32_e32 v204, 0xbfb8aa3b, v182
	v_mul_f32_e32 v205, 0xbfb8aa3b, v183
	v_exp_f32_e32 v204, v204
	v_exp_f32_e32 v205, v205
	v_pk_add_f32 v[186:187], v[186:187], 1.0 op_sel_hi:[1,0]
	v_pk_add_f32 v[204:205], v[204:205], 1.0 op_sel_hi:[1,0]
	v_rcp_f32_e32 v186, v186
	v_rcp_f32_e32 v187, v187
	v_rcp_f32_e32 v204, v204
	v_rcp_f32_e32 v205, v205
	v_pk_mul_f32 v[184:185], v[184:185], v[186:187]
	s_nop 0
	v_cndmask_b32_e64 v185, v187, v185, s[0:1]
	v_pk_mul_f32 v[182:183], v[182:183], v[204:205]
	v_cndmask_b32_e64 v184, v186, v184, s[0:1]
	v_mov_b64_e32 v[186:187], s[6:7]
	v_cndmask_b32_e64 v205, v205, v183, s[0:1]
	v_cndmask_b32_e64 v204, v204, v182, s[0:1]
	v_mad_i64_i32 v[186:187], s[10:11], v181, s10, v[186:187]
	v_cvt_pk_bf16_f32 v182, v203, v201
	v_cvt_pk_bf16_f32 v183, v199, v197
	v_cvt_pk_bf16_f32 v184, v184, v185
	v_cvt_pk_bf16_f32 v185, v204, v205
	v_lshl_add_u64 v[186:187], v[4:5], 1, v[186:187]
	global_store_dwordx4 v[186:187], v[182:185], off
